# P1 weight conversion (WIN/WMI/WMO): loop rotated, next item's loads issued before the LDS read/convert/store phase, counted vmcnt(4)
# speedup vs baseline: 1.0005x; 1.0005x over previous
.LBB0_22:
	s_or_b64 exec, exec, s[44:45]
	s_waitcnt vmcnt(0)
	s_branch .Lp1w1_wb

.Lp1w1_wb:
	ds_write2_b32 v41, v4, v5 offset1:1
	ds_write2_b32 v41, v6, v7 offset0:2 offset1:3
	v_add_u32_e32 v4, 0x2080, v41
	ds_write2_b32 v4, v0, v1 offset1:1
	v_add_u32_e32 v0, 0x2088, v41
	ds_write2_b32 v0, v2, v3 offset1:1
	v_add_u32_e32 v0, 0x4100, v41
	ds_write2_b32 v0, v12, v13 offset1:1
	v_add_u32_e32 v0, 0x4108, v41
	ds_write2_b32 v0, v14, v15 offset1:1
	v_add_u32_e32 v0, 0x6180, v41
	ds_write2_b32 v0, v8, v9 offset1:1
	v_add_u32_e32 v0, 0x6188, v41
	ds_write2_b32 v0, v10, v11 offset1:1
	v_add_u32_e32 v0, 0x8200, v41
	ds_write2_b32 v0, v20, v21 offset1:1
	v_add_u32_e32 v0, 0x8208, v41
	ds_write2_b32 v0, v22, v23 offset1:1
	v_add_u32_e32 v0, 0xa280, v41
	ds_write2_b32 v0, v16, v17 offset1:1
	v_add_u32_e32 v0, 0xa288, v41
	ds_write2_b32 v0, v18, v19 offset1:1
	v_add_u32_e32 v0, 0xc300, v41
	ds_write2_b32 v0, v28, v29 offset1:1
	v_add_u32_e32 v0, 0xc308, v41
	ds_write2_b32 v0, v30, v31 offset1:1
	v_add_u32_e32 v0, 0xe380, v41
	ds_write2_b32 v0, v24, v25 offset1:1
	v_add_u32_e32 v0, 0xe388, v41
	v_add_u32_e32 v205, 0x400, v37
	ds_write2_b32 v0, v26, v27 offset1:1
	v_readlane_b32 s10, v250, 11
	s_mov_b32 s98, s0
	s_mov_b32 s100, s36
	s_add_i32 s46, s46, s10
	s_cmpk_lt_i32 s46, 0x400
	s_cselect_b32 s101, 1, 0
	s_cbranch_scc0 .Lp1w1_b1j
	s_ashr_i32 s0, s46, 31
	s_lshr_b32 s0, s0, 22
	s_add_i32 s0, s46, s0
	s_and_b32 s0, s0, 0xfc00
	s_sub_i32 s0, s46, s0
	s_sext_i32_i16 s1, s0
	s_bfe_u32 s1, s1, 0x5001a
	s_add_i32 s1, s0, s1
	s_sext_i32_i16 s36, s1
	s_and_b32 s1, s1, 0xffe0
	s_sub_i32 s0, s0, s1
	s_lshl_b32 s1, s36, 3
	s_and_b32 s36, s1, 0xffffff00
	s_sext_i32_i16 s0, s0
	s_ashr_i32 s37, s36, 31
	s_lshl_b32 s0, s0, 6
	s_lshl_b64 s[42:43], s[36:37], 2
	s_add_u32 s42, s47, s42
	v_or_b32_e32 v0, s36, v32
	s_movk_i32 s1, 0x1f48
	v_add_u32_e32 v25, s0, v33
	s_addc_u32 s43, s48, s43
	v_cmp_gt_i32_e32 vcc, s1, v0
	v_mov_b32_e32 v0, 0
	v_lshlrev_b32_e32 v168, 2, v32
	v_mov_b32_e32 v4, 0
	v_mov_b32_e32 v5, 0
	v_mov_b32_e32 v6, 0
	v_mov_b32_e32 v7, 0
	s_and_saveexec_b64 s[44:45], vcc
	s_cbranch_execz .Lp1w1_25
	v_mov_b64_e32 v[2:3], s[42:43]
	s_movk_i32 s1, 0x7d20
	v_mad_i64_i32 v[2:3], s[50:51], v25, s1, v[2:3]
	v_lshl_add_u64 v[2:3], v[2:3], 0, v[168:169]
	global_load_dwordx4 v[4:7], v[2:3], off nt

.Lp1w1_37:
	s_or_b64 exec, exec, s[44:45]
	v_mov_b32_e32 v25, 0
	v_mov_b32_e32 v26, 0
	v_mov_b32_e32 v27, 0
	s_and_saveexec_b64 s[44:45], vcc
	s_cbranch_execz .Lp1w1_b1
	v_mov_b64_e32 v[24:25], s[42:43]
	s_movk_i32 s1, 0x7d20
	v_mad_i64_i32 v[24:25], s[42:43], v42, s1, v[24:25]
	v_lshl_add_u64 v[24:25], v[24:25], 0, v[168:169]
	global_load_dwordx4 v[24:27], v[24:25], off offset:768 nt
	s_branch .Lp1w1_b1
.Lp1w1_b1:
	s_or_b64 exec, exec, s[44:45]
.Lp1w1_b1j:
	s_waitcnt lgkmcnt(0)
	s_barrier
	ds_read2_b32 v[200:201], v37 offset1:65
	ds_read2_b32 v[202:203], v37 offset0:130 offset1:195
	ds_read2_b32 v[206:207], v205 offset0:4 offset1:69
	ds_read2_b32 v[208:209], v205 offset0:134 offset1:199
	v_add_u32_e32 v204, s100, v36
	s_ashr_i32 s99, s98, 31
	v_ashrrev_i32_e32 v205, 31, v204
	v_lshl_add_u64 v[210:211], s[98:99], 1, v[34:35]
	s_waitcnt lgkmcnt(3)
	v_cvt_pk_bf16_f32 v200, v200, v201
	s_waitcnt lgkmcnt(2)
	v_cvt_pk_bf16_f32 v201, v202, v203
	s_waitcnt lgkmcnt(0)
	v_cvt_pk_bf16_f32 v203, v208, v209
	v_lshlrev_b64 v[204:205], 12, v[204:205]
	v_add_u32_e32 v208, 0x4200, v37
	v_add_u32_e32 v212, 0x4600, v37
	v_lshl_add_u64 v[204:205], v[210:211], 0, v[204:205]
	ds_read2_b32 v[208:209], v208 offset0:66 offset1:131
	v_add_u32_e32 v210, 0x4400, v37
	ds_read2_b32 v[212:213], v212 offset0:70 offset1:135
	ds_read2_b32 v[210:211], v210 offset0:68 offset1:133
	v_cvt_pk_bf16_f32 v202, v206, v207
	v_add_u32_e32 v206, 0x4000, v37
	ds_read2_b32 v[206:207], v206 offset0:64 offset1:129
	global_store_dwordx4 v[204:205], v[200:203], off
	v_add_u32_e32 v214, 0x8800, v37
	s_mov_b32 s98, 0x40000
	s_waitcnt lgkmcnt(3)
	v_cvt_pk_bf16_f32 v201, v208, v209
	s_waitcnt lgkmcnt(2)
	v_cvt_pk_bf16_f32 v203, v212, v213
	v_add_u32_e32 v208, 0x8000, v37
	v_add_u32_e32 v212, 0x8400, v37
	s_waitcnt lgkmcnt(1)
	v_cvt_pk_bf16_f32 v202, v210, v211
	ds_read2_b32 v[208:209], v208 offset0:128 offset1:193
	ds_read2_b32 v[210:211], v212 offset0:2 offset1:67
	ds_read2_b32 v[212:213], v212 offset0:132 offset1:197
	ds_read2_b32 v[214:215], v214 offset0:6 offset1:71
	s_waitcnt lgkmcnt(4)
	v_cvt_pk_bf16_f32 v200, v206, v207
	v_add_co_u32_e32 v206, vcc, s98, v204
	s_mov_b32 s98, 0x80000
	s_nop 0
	v_addc_co_u32_e32 v207, vcc, 0, v205, vcc
	global_store_dwordx4 v[206:207], v[200:203], off
	v_add_co_u32_e32 v206, vcc, s98, v204
	s_waitcnt lgkmcnt(3)
	v_cvt_pk_bf16_f32 v200, v208, v209
	s_waitcnt lgkmcnt(2)
	v_cvt_pk_bf16_f32 v201, v210, v211
	s_waitcnt lgkmcnt(1)
	v_cvt_pk_bf16_f32 v202, v212, v213
	s_waitcnt lgkmcnt(0)
	v_cvt_pk_bf16_f32 v203, v214, v215
	v_add_u32_e32 v208, 0xc200, v37
	v_add_u32_e32 v210, 0xc400, v37
	v_add_u32_e32 v212, 0xc600, v37
	v_add_u32_e32 v214, 0xc800, v37
	ds_read2_b32 v[208:209], v208 offset0:64 offset1:129
	ds_read2_b32 v[210:211], v210 offset0:66 offset1:131
	ds_read2_b32 v[212:213], v212 offset0:68 offset1:133
	ds_read2_b32 v[214:215], v214 offset0:70 offset1:135
	v_readlane_b32 s4, v250, 5
	v_addc_co_u32_e32 v207, vcc, 0, v205, vcc
	v_readlane_b32 s10, v250, 11
	v_add_co_u32_e32 v204, vcc, 0xc0000, v204
	global_store_dwordx4 v[206:207], v[200:203], off
	v_addc_co_u32_e32 v205, vcc, 0, v205, vcc
	s_waitcnt lgkmcnt(3)
	v_cvt_pk_bf16_f32 v200, v208, v209
	s_waitcnt lgkmcnt(2)
	v_cvt_pk_bf16_f32 v201, v210, v211
	s_waitcnt lgkmcnt(1)
	v_cvt_pk_bf16_f32 v202, v212, v213
	s_waitcnt lgkmcnt(0)
	v_cvt_pk_bf16_f32 v203, v214, v215
	global_store_dwordx4 v[204:205], v[200:203], off
	s_barrier
	v_readlane_b32 s5, v250, 6
	v_readlane_b32 s6, v250, 7
	v_readlane_b32 s7, v250, 8
	v_readlane_b32 s8, v250, 9
	v_readlane_b32 s9, v250, 10
	v_readlane_b32 s11, v250, 12
	s_cmp_lg_u32 s101, 0
	s_cbranch_scc1 .Lp1w1_wl
	s_branch .LBB0_39

.LBB0_105:
	s_or_b64 exec, exec, s[48:49]
	s_waitcnt vmcnt(0)
	s_branch .Lp1w7_wb

.Lp1w7_wb:
	ds_write2_b32 v43, v4, v5 offset1:1
	ds_write2_b32 v43, v6, v7 offset0:2 offset1:3
	v_add_u32_e32 v4, 0x2080, v43
	ds_write2_b32 v4, v0, v1 offset1:1
	v_add_u32_e32 v0, 0x2088, v43
	ds_write2_b32 v0, v2, v3 offset1:1
	v_add_u32_e32 v0, 0x4100, v43
	ds_write2_b32 v0, v8, v9 offset1:1
	v_add_u32_e32 v0, 0x4108, v43
	ds_write2_b32 v0, v10, v11 offset1:1
	v_add_u32_e32 v0, 0x6180, v43
	ds_write2_b32 v0, v12, v13 offset1:1
	v_add_u32_e32 v0, 0x6188, v43
	ds_write2_b32 v0, v14, v15 offset1:1
	v_add_u32_e32 v0, 0x8200, v43
	ds_write2_b32 v0, v16, v17 offset1:1
	v_add_u32_e32 v0, 0x8208, v43
	ds_write2_b32 v0, v18, v19 offset1:1
	v_add_u32_e32 v0, 0xa280, v43
	ds_write2_b32 v0, v20, v21 offset1:1
	v_add_u32_e32 v0, 0xa288, v43
	ds_write2_b32 v0, v22, v23 offset1:1
	v_add_u32_e32 v0, 0xc300, v43
	ds_write2_b32 v0, v24, v25 offset1:1
	v_add_u32_e32 v0, 0xc308, v43
	ds_write2_b32 v0, v26, v27 offset1:1
	v_add_u32_e32 v0, 0xe380, v43
	ds_write2_b32 v0, v28, v29 offset1:1
	v_add_u32_e32 v0, 0xe388, v43
	v_add_u32_e32 v205, 0x400, v39
	ds_write2_b32 v0, v30, v31 offset1:1
	v_readlane_b32 s10, v250, 11
	s_mov_b32 s98, s42
	s_mov_b32 s100, s44
	s_add_i32 s50, s50, s10
	s_cmpk_lt_i32 s50, 0x400
	s_cselect_b32 s101, 1, 0
	s_cbranch_scc0 .Lp1w7_b1j
	s_ashr_i32 s42, s50, 31
	s_lshr_b32 s42, s42, 22
	s_add_i32 s42, s50, s42
	s_and_b32 s42, s42, 0xfc00
	s_sub_i32 s42, s50, s42
	s_sext_i32_i16 s43, s42
	s_bfe_u32 s43, s43, 0x5001a
	s_add_i32 s43, s42, s43
	s_sext_i32_i16 s44, s43
	s_and_b32 s43, s43, 0xffe0
	s_sub_i32 s42, s42, s43
	s_lshl_b32 s43, s44, 3
	s_and_b32 s44, s43, 0xffffff00
	s_sext_i32_i16 s42, s42
	s_ashr_i32 s45, s44, 31
	s_lshl_b32 s42, s42, 6
	s_lshl_b64 s[46:47], s[44:45], 2
	v_add_u32_e32 v36, s42, v33
	s_add_u32 s46, s51, s46
	v_or_b32_e32 v0, s44, v32
	s_movk_i32 s4, 0x2000
	s_addc_u32 s47, s58, s47
	v_cmp_gt_i32_e32 vcc, s4, v0
	v_mov_b32_e32 v0, 0
	v_ashrrev_i32_e32 v37, 31, v36
	v_lshlrev_b32_e32 v168, 2, v32
	v_mov_b32_e32 v4, 0
	v_mov_b32_e32 v5, 0
	v_mov_b32_e32 v6, 0
	v_mov_b32_e32 v7, 0
	s_and_saveexec_b64 s[48:49], vcc
	s_cbranch_execz .Lp1w7_108
	v_lshlrev_b64 v[2:3], 15, v[36:37]
	v_lshl_add_u64 v[2:3], s[46:47], 0, v[2:3]
	v_lshl_add_u64 v[2:3], v[2:3], 0, v[168:169]
	global_load_dwordx4 v[4:7], v[2:3], off nt

.Lp1w7_120:
	s_or_b64 exec, exec, s[48:49]
	v_mov_b32_e32 v29, 0
	v_mov_b32_e32 v30, 0
	v_mov_b32_e32 v31, 0
	s_and_saveexec_b64 s[48:49], vcc
	s_cbranch_execz .Lp1w7_b1
	v_lshlrev_b64 v[28:29], 15, v[36:37]
	v_lshl_add_u64 v[28:29], s[46:47], 0, v[28:29]
	v_lshl_add_u64 v[28:29], v[28:29], 0, v[168:169]
	v_add_co_u32_e32 v28, vcc, 0x100000, v28
	s_nop 1
	v_addc_co_u32_e32 v29, vcc, 0, v29, vcc
	global_load_dwordx4 v[28:31], v[28:29], off offset:768 nt
	s_branch .Lp1w7_b1
.Lp1w7_b1:
	s_or_b64 exec, exec, s[48:49]
.Lp1w7_b1j:
	s_waitcnt lgkmcnt(0)
	s_barrier
	ds_read2_b32 v[200:201], v39 offset1:65
	ds_read2_b32 v[202:203], v39 offset0:130 offset1:195
	ds_read2_b32 v[206:207], v205 offset0:4 offset1:69
	ds_read2_b32 v[208:209], v205 offset0:134 offset1:199
	v_add_u32_e32 v204, s100, v38
	s_ashr_i32 s99, s98, 31
	v_ashrrev_i32_e32 v205, 31, v204
	v_lshl_add_u64 v[210:211], s[98:99], 1, v[34:35]
	s_waitcnt lgkmcnt(3)
	v_cvt_pk_bf16_f32 v200, v200, v201
	s_waitcnt lgkmcnt(2)
	v_cvt_pk_bf16_f32 v201, v202, v203
	s_waitcnt lgkmcnt(0)
	v_cvt_pk_bf16_f32 v203, v208, v209
	v_lshlrev_b64 v[204:205], 12, v[204:205]
	v_add_u32_e32 v208, 0x4200, v39
	v_add_u32_e32 v212, 0x4600, v39
	v_lshl_add_u64 v[204:205], v[210:211], 0, v[204:205]
	ds_read2_b32 v[208:209], v208 offset0:66 offset1:131
	v_add_u32_e32 v210, 0x4400, v39
	ds_read2_b32 v[212:213], v212 offset0:70 offset1:135
	ds_read2_b32 v[210:211], v210 offset0:68 offset1:133
	v_cvt_pk_bf16_f32 v202, v206, v207
	v_add_u32_e32 v206, 0x4000, v39
	ds_read2_b32 v[206:207], v206 offset0:64 offset1:129
	global_store_dwordx4 v[204:205], v[200:203], off
	v_add_u32_e32 v214, 0x8800, v39
	s_mov_b32 s4, 0x40000
	s_waitcnt lgkmcnt(3)
	v_cvt_pk_bf16_f32 v201, v208, v209
	s_waitcnt lgkmcnt(2)
	v_cvt_pk_bf16_f32 v203, v212, v213
	v_add_u32_e32 v208, 0x8000, v39
	v_add_u32_e32 v212, 0x8400, v39
	s_waitcnt lgkmcnt(1)
	v_cvt_pk_bf16_f32 v202, v210, v211
	ds_read2_b32 v[208:209], v208 offset0:128 offset1:193
	ds_read2_b32 v[210:211], v212 offset0:2 offset1:67
	ds_read2_b32 v[212:213], v212 offset0:132 offset1:197
	ds_read2_b32 v[214:215], v214 offset0:6 offset1:71
	s_waitcnt lgkmcnt(4)
	v_cvt_pk_bf16_f32 v200, v206, v207
	v_add_co_u32_e32 v206, vcc, s4, v204
	s_mov_b32 s4, 0x80000
	s_nop 0
	v_addc_co_u32_e32 v207, vcc, 0, v205, vcc
	global_store_dwordx4 v[206:207], v[200:203], off
	v_add_co_u32_e32 v206, vcc, s4, v204
	s_waitcnt lgkmcnt(3)
	v_cvt_pk_bf16_f32 v200, v208, v209
	s_waitcnt lgkmcnt(2)
	v_cvt_pk_bf16_f32 v201, v210, v211
	s_waitcnt lgkmcnt(1)
	v_cvt_pk_bf16_f32 v202, v212, v213
	s_waitcnt lgkmcnt(0)
	v_cvt_pk_bf16_f32 v203, v214, v215
	v_add_u32_e32 v208, 0xc200, v39
	v_add_u32_e32 v210, 0xc400, v39
	v_add_u32_e32 v212, 0xc600, v39
	v_add_u32_e32 v214, 0xc800, v39
	ds_read2_b32 v[208:209], v208 offset0:64 offset1:129
	ds_read2_b32 v[210:211], v210 offset0:66 offset1:131
	ds_read2_b32 v[212:213], v212 offset0:68 offset1:133
	ds_read2_b32 v[214:215], v214 offset0:70 offset1:135
	v_readlane_b32 s4, v250, 5
	v_addc_co_u32_e32 v207, vcc, 0, v205, vcc
	v_readlane_b32 s10, v250, 11
	v_add_co_u32_e32 v204, vcc, 0xc0000, v204
	global_store_dwordx4 v[206:207], v[200:203], off
	v_addc_co_u32_e32 v205, vcc, 0, v205, vcc
	s_waitcnt lgkmcnt(3)
	v_cvt_pk_bf16_f32 v200, v208, v209
	s_waitcnt lgkmcnt(2)
	v_cvt_pk_bf16_f32 v201, v210, v211
	s_waitcnt lgkmcnt(1)
	v_cvt_pk_bf16_f32 v202, v212, v213
	s_waitcnt lgkmcnt(0)
	v_cvt_pk_bf16_f32 v203, v214, v215
	global_store_dwordx4 v[204:205], v[200:203], off
	s_barrier
	v_readlane_b32 s5, v250, 6
	v_readlane_b32 s6, v250, 7
	v_readlane_b32 s7, v250, 8
	v_readlane_b32 s8, v250, 9
	v_readlane_b32 s9, v250, 10
	v_readlane_b32 s11, v250, 12
	s_cmp_lg_u32 s101, 0
	s_cbranch_scc1 .Lp1w7_wl
	s_branch .LBB0_122

.LBB0_124:
	s_or_b64 exec, exec, s[46:47]
	s_waitcnt vmcnt(0)
	s_branch .Lp1w8_wb

.Lp1w8_wb:
	ds_write2_b32 v43, v4, v5 offset1:1
	ds_write2_b32 v43, v6, v7 offset0:2 offset1:3
	v_add_u32_e32 v4, 0x2080, v43
	ds_write2_b32 v4, v0, v1 offset1:1
	v_add_u32_e32 v0, 0x2088, v43
	ds_write2_b32 v0, v2, v3 offset1:1
	v_add_u32_e32 v0, 0x4100, v43
	ds_write2_b32 v0, v8, v9 offset1:1
	v_add_u32_e32 v0, 0x4108, v43
	ds_write2_b32 v0, v10, v11 offset1:1
	v_add_u32_e32 v0, 0x6180, v43
	ds_write2_b32 v0, v12, v13 offset1:1
	v_add_u32_e32 v0, 0x6188, v43
	ds_write2_b32 v0, v14, v15 offset1:1
	v_add_u32_e32 v0, 0x8200, v43
	ds_write2_b32 v0, v16, v17 offset1:1
	v_add_u32_e32 v0, 0x8208, v43
	ds_write2_b32 v0, v18, v19 offset1:1
	v_add_u32_e32 v0, 0xa280, v43
	ds_write2_b32 v0, v20, v21 offset1:1
	v_add_u32_e32 v0, 0xa288, v43
	ds_write2_b32 v0, v22, v23 offset1:1
	v_add_u32_e32 v0, 0xc300, v43
	ds_write2_b32 v0, v24, v25 offset1:1
	v_add_u32_e32 v0, 0xc308, v43
	ds_write2_b32 v0, v26, v27 offset1:1
	v_add_u32_e32 v0, 0xe380, v43
	ds_write2_b32 v0, v28, v29 offset1:1
	v_add_u32_e32 v0, 0xe388, v43
	v_add_u32_e32 v205, 0x400, v39
	ds_write2_b32 v0, v30, v31 offset1:1
	v_readlane_b32 s10, v250, 11
	s_mov_b32 s98, s0
	s_mov_b32 s100, s42
	s_add_i32 s48, s48, s10
	s_cmpk_lt_i32 s48, 0x400
	s_cselect_b32 s101, 1, 0
	s_cbranch_scc0 .Lp1w8_b1j
	s_ashr_i32 s0, s48, 31
	s_lshr_b32 s0, s0, 22
	s_add_i32 s0, s48, s0
	s_and_b32 s0, s0, 0xfc00
	s_sub_i32 s0, s48, s0
	s_sext_i32_i16 s1, s0
	s_bfe_u32 s1, s1, 0x70018
	s_add_i32 s1, s0, s1
	s_sext_i32_i16 s42, s1
	s_and_b32 s1, s1, 0xff80
	s_sub_i32 s0, s0, s1
	s_lshl_b32 s1, s42, 1
	s_and_b32 s42, s1, 0xffffff00
	s_sext_i32_i16 s0, s0
	s_ashr_i32 s43, s42, 31
	s_lshl_b32 s0, s0, 6
	s_lshl_b64 s[44:45], s[42:43], 2
	v_add_u32_e32 v36, s0, v33
	s_add_u32 s44, s49, s44
	v_or_b32_e32 v0, s42, v32
	s_movk_i32 s1, 0x800
	s_addc_u32 s45, s50, s45
	v_cmp_gt_i32_e32 vcc, s1, v0
	v_mov_b32_e32 v0, 0
	v_ashrrev_i32_e32 v37, 31, v36
	v_lshlrev_b32_e32 v168, 2, v32
	v_mov_b32_e32 v4, 0
	v_mov_b32_e32 v5, 0
	v_mov_b32_e32 v6, 0
	v_mov_b32_e32 v7, 0
	s_and_saveexec_b64 s[46:47], vcc
	s_cbranch_execz .Lp1w8_127
	v_lshlrev_b64 v[2:3], 13, v[36:37]
	v_lshl_add_u64 v[2:3], s[44:45], 0, v[2:3]
	v_lshl_add_u64 v[2:3], v[2:3], 0, v[168:169]
	global_load_dwordx4 v[4:7], v[2:3], off nt

.Lp1w8_139:
	s_or_b64 exec, exec, s[46:47]
	v_mov_b32_e32 v29, 0
	v_mov_b32_e32 v30, 0
	v_mov_b32_e32 v31, 0
	s_and_saveexec_b64 s[46:47], vcc
	s_cbranch_execz .Lp1w8_b1
	v_lshlrev_b64 v[28:29], 13, v[36:37]
	v_lshl_add_u64 v[28:29], s[44:45], 0, v[28:29]
	v_lshl_add_u64 v[28:29], v[28:29], 0, v[168:169]
	v_add_co_u32_e32 v28, vcc, 0x40000, v28
	s_nop 1
	v_addc_co_u32_e32 v29, vcc, 0, v29, vcc
	global_load_dwordx4 v[28:31], v[28:29], off offset:768 nt
	s_branch .Lp1w8_b1
.Lp1w8_b1:
	s_or_b64 exec, exec, s[46:47]
.Lp1w8_b1j:
	s_waitcnt lgkmcnt(0)
	s_barrier
	ds_read2_b32 v[200:201], v39 offset1:65
	ds_read2_b32 v[202:203], v39 offset0:130 offset1:195
	ds_read2_b32 v[206:207], v205 offset0:4 offset1:69
	ds_read2_b32 v[208:209], v205 offset0:134 offset1:199
	v_add_u32_e32 v204, s100, v38
	s_ashr_i32 s99, s98, 31
	v_ashrrev_i32_e32 v205, 31, v204
	v_lshl_add_u64 v[210:211], s[98:99], 1, v[34:35]
	s_waitcnt lgkmcnt(3)
	v_cvt_pk_bf16_f32 v200, v200, v201
	s_waitcnt lgkmcnt(2)
	v_cvt_pk_bf16_f32 v201, v202, v203
	s_waitcnt lgkmcnt(0)
	v_cvt_pk_bf16_f32 v203, v208, v209
	v_lshlrev_b64 v[204:205], 14, v[204:205]
	v_add_u32_e32 v208, 0x4200, v39
	v_add_u32_e32 v212, 0x4600, v39
	v_lshl_add_u64 v[204:205], v[210:211], 0, v[204:205]
	ds_read2_b32 v[208:209], v208 offset0:66 offset1:131
	v_add_u32_e32 v210, 0x4400, v39
	ds_read2_b32 v[212:213], v212 offset0:70 offset1:135
	ds_read2_b32 v[210:211], v210 offset0:68 offset1:133
	v_cvt_pk_bf16_f32 v202, v206, v207
	v_add_u32_e32 v206, 0x4000, v39
	ds_read2_b32 v[206:207], v206 offset0:64 offset1:129
	global_store_dwordx4 v[204:205], v[200:203], off
	v_add_u32_e32 v214, 0x8800, v39
	s_mov_b32 s98, 0x100000
	s_waitcnt lgkmcnt(3)
	v_cvt_pk_bf16_f32 v201, v208, v209
	s_waitcnt lgkmcnt(2)
	v_cvt_pk_bf16_f32 v203, v212, v213
	v_add_u32_e32 v208, 0x8000, v39
	v_add_u32_e32 v212, 0x8400, v39
	s_waitcnt lgkmcnt(1)
	v_cvt_pk_bf16_f32 v202, v210, v211
	ds_read2_b32 v[208:209], v208 offset0:128 offset1:193
	ds_read2_b32 v[210:211], v212 offset0:2 offset1:67
	ds_read2_b32 v[212:213], v212 offset0:132 offset1:197
	ds_read2_b32 v[214:215], v214 offset0:6 offset1:71
	s_waitcnt lgkmcnt(4)
	v_cvt_pk_bf16_f32 v200, v206, v207
	v_add_co_u32_e32 v206, vcc, s98, v204
	s_mov_b32 s98, 0x200000
	s_nop 0
	v_addc_co_u32_e32 v207, vcc, 0, v205, vcc
	global_store_dwordx4 v[206:207], v[200:203], off
	v_add_co_u32_e32 v206, vcc, s98, v204
	s_waitcnt lgkmcnt(3)
	v_cvt_pk_bf16_f32 v200, v208, v209
	s_waitcnt lgkmcnt(2)
	v_cvt_pk_bf16_f32 v201, v210, v211
	s_waitcnt lgkmcnt(1)
	v_cvt_pk_bf16_f32 v202, v212, v213
	s_waitcnt lgkmcnt(0)
	v_cvt_pk_bf16_f32 v203, v214, v215
	v_add_u32_e32 v208, 0xc200, v39
	v_add_u32_e32 v210, 0xc400, v39
	v_add_u32_e32 v212, 0xc600, v39
	v_add_u32_e32 v214, 0xc800, v39
	ds_read2_b32 v[208:209], v208 offset0:64 offset1:129
	ds_read2_b32 v[210:211], v210 offset0:66 offset1:131
	ds_read2_b32 v[212:213], v212 offset0:68 offset1:133
	ds_read2_b32 v[214:215], v214 offset0:70 offset1:135
	v_readlane_b32 s4, v250, 5
	v_addc_co_u32_e32 v207, vcc, 0, v205, vcc
	v_readlane_b32 s10, v250, 11
	v_add_co_u32_e32 v204, vcc, 0x300000, v204
	global_store_dwordx4 v[206:207], v[200:203], off
	v_addc_co_u32_e32 v205, vcc, 0, v205, vcc
	s_waitcnt lgkmcnt(3)
	v_cvt_pk_bf16_f32 v200, v208, v209
	s_waitcnt lgkmcnt(2)
	v_cvt_pk_bf16_f32 v201, v210, v211
	s_waitcnt lgkmcnt(1)
	v_cvt_pk_bf16_f32 v202, v212, v213
	s_waitcnt lgkmcnt(0)
	v_cvt_pk_bf16_f32 v203, v214, v215
	global_store_dwordx4 v[204:205], v[200:203], off
	s_barrier
	v_readlane_b32 s5, v250, 6
	v_readlane_b32 s6, v250, 7
	v_readlane_b32 s7, v250, 8
	v_readlane_b32 s8, v250, 9
	v_readlane_b32 s9, v250, 10
	v_readlane_b32 s11, v250, 12
	s_cmp_lg_u32 s101, 0
	s_cbranch_scc1 .Lp1w8_wl
	s_branch .LBB0_141
